# P11: prefetch next-token scores, hoist CAND/g2/b2 loads, early x reload
# baseline (speedup 1.0000x reference)
; DEVI int ltid() { int t = threadIdx.x; asm volatile("" : "+v"(t)); return t; }
; DEVI void phase11(const Params& P, int l, int pass, char* smem) {
;   const int ntok = pass ? 8192 : 8448, base = pass ? 8448 : 0;
;   const int tid = ltid(); const int w = tid >> 6, lane = tid & 63;
;   float* scl = (float*)smem;
;   float* sv = scl + 2048;
;   int* si = (int*)(sv + 256);
;   float* tops = (float*)(si + 256);
;   int* tope = (int*)(tops + 128);
;   float* wgt = (float*)(tope + 128);
;   float* svs = wgt + 128;
;   int* sis = (int*)(svs + 256);
;   float* red = (float*)(sis + 256);
;   float* stat = red + 4096;
;   const float* SC = (const float*)(P.ws + O_AU);
;   const unsigned char* UT = (const unsigned char*)(P.ws + O_UTB);
;   const unsigned char* VTb = (const unsigned char*)(P.ws + O_VTB);
;   const float* g2 = P.in[28] + l * 1024;
;   const float* b2 = P.in[29] + l * 1024;
;   bfu* xb = (bfu*)(P.ws + O_XB);
;   const unsigned long long ltmask = (1ull << lane) - 1ull;
;   for (int lt = blockIdx.x; lt < ntok; lt += gridDim.x) {
;     const int it = base + lt;
;     float* xr = xrow(P, it);
;     __syncthreads();
;     {
;       unsigned long long* s8 = reinterpret_cast<unsigned long long*>(const_cast<float*>(SC) + (long)lt * 2048);
;       unsigned long long* d8 = reinterpret_cast<unsigned long long*>(scl);
; #pragma unroll
;       for (int q = 0; q < 4; ++q)
;         d8[tid + 256 * q] = __hip_atomic_load(s8 + tid + 256 * q, __ATOMIC_RELAXED, __HIP_MEMORY_SCOPE_AGENT);
;     }
.LBB0_125:
	s_andn2_b64 vcc, exec, s[26:27]
	s_mov_b32 s0, s2
	s_cbranch_vccnz .LBB0_276
	s_add_i32 s1, s51, -1
	s_mov_b32 s0, s2
	s_cmp_eq_u32 s1, 0
	s_cselect_b64 s[40:41], -1, 0
	s_and_b64 s[42:43], s[40:41], exec
	s_movk_i32 s1, 0x2100
	s_cselect_b32 s1, s1, 0x2000
	v_readlane_b32 s58, v252, 32
	v_mov_b32_e32 v0, v93
	s_cmp_ge_i32 s58, s1
	s_cbranch_scc1 .LBB0_276
	v_and_b32_e32 v88, 63, v0
	v_lshlrev_b64 v[2:3], v0, -1
	v_not_b32_e32 v91, v3
	v_not_b32_e32 v100, v2
	v_lshlrev_b32_e32 v2, 4, v88
	v_mov_b32_e32 v3, v89
	v_lshl_add_u64 v[110:111], v[70:71], 0, v[2:3]
	v_lshl_add_u64 v[112:113], v[68:69], 0, v[2:3]
	v_and_b32_e32 v3, 32, v0
	v_and_b32_e32 v4, 64, v187
	v_cmp_eq_u32_e64 s[44:45], 0, v3
	v_xor_b32_e32 v3, 32, v187
	v_add_u32_e32 v4, 64, v4
	v_cmp_lt_i32_e32 vcc, v3, v4
	v_and_b32_e32 v7, 15, v0
	s_and_b64 s[40:41], s[40:41], exec
	v_cndmask_b32_e32 v3, v187, v3, vcc
	v_lshlrev_b32_e32 v125, 2, v3
	v_and_b32_e32 v3, 16, v0
	v_cmp_eq_u32_e64 s[46:47], 0, v3
	v_xor_b32_e32 v3, 16, v187
	v_cmp_lt_i32_e32 vcc, v3, v4
	s_cselect_b32 s82, 0, 0x2100
	s_lshl_b32 s40, s0, 10
	v_cndmask_b32_e32 v3, v187, v3, vcc
	v_lshlrev_b32_e32 v126, 2, v3
	v_and_b32_e32 v3, 8, v0
	v_cmp_eq_u32_e64 s[48:49], 0, v3
	v_xor_b32_e32 v3, 8, v187
	v_cmp_lt_i32_e32 vcc, v3, v4
	s_ashr_i32 s41, s40, 31
	v_readlane_b32 s4, v253, 14
	v_cndmask_b32_e32 v3, v187, v3, vcc
	v_lshlrev_b32_e32 v127, 2, v3
	v_xor_b32_e32 v3, 4, v187
	v_cmp_lt_i32_e32 vcc, v3, v4
	s_lshl_b64 s[40:41], s[40:41], 2
	v_readlane_b32 s18, v253, 28
	v_cndmask_b32_e32 v3, v187, v3, vcc
	v_lshlrev_b32_e32 v128, 2, v3
	v_xor_b32_e32 v3, 2, v187
	v_cmp_lt_i32_e32 vcc, v3, v4
	v_readlane_b32 s19, v253, 29
	s_add_u32 s54, s18, s40
	v_cndmask_b32_e32 v3, v187, v3, vcc
	v_lshlrev_b32_e32 v129, 2, v3
	v_xor_b32_e32 v3, 1, v187
	v_cmp_lt_i32_e32 vcc, v3, v4
	v_readlane_b32 s16, v253, 26
	s_addc_u32 s55, s19, s41
	v_cndmask_b32_e32 v3, v187, v3, vcc
	v_cmp_ne_u32_e32 vcc, 0, v7
	v_readlane_b32 s17, v253, 27
	s_add_u32 s56, s16, s40
	v_cndmask_b32_e64 v132, 0, 1, vcc
	v_cmp_lt_u32_e32 vcc, 1, v7
	v_ashrrev_i32_e32 v6, 6, v0
	s_addc_u32 s57, s17, s41
	v_cndmask_b32_e64 v133, 0, 1, vcc
	v_cmp_lt_u32_e32 vcc, 2, v7
	v_and_b32_e32 v109, 0xffffffc0, v0
	v_lshlrev_b32_e32 v104, 2, v0
	v_cndmask_b32_e64 v134, 0, 1, vcc
	v_cmp_lt_u32_e32 vcc, 3, v7
	v_lshlrev_b32_e32 v108, 7, v6
	s_movk_i32 s24, 0xf80
	v_cndmask_b32_e64 v135, 0, 1, vcc
	v_cmp_lt_u32_e32 vcc, 4, v7
	v_readlane_b32 s6, v253, 16
	v_readlane_b32 s7, v253, 17
	v_cndmask_b32_e64 v136, 0, 1, vcc
	v_cmp_lt_u32_e32 vcc, 5, v7
	v_ashrrev_i32_e32 v1, 31, v0
	v_lshlrev_b32_e32 v101, 3, v0
	v_cndmask_b32_e64 v137, 0, 1, vcc
	v_cmp_lt_u32_e32 vcc, 6, v7
	s_getpc_b64 s[42:43]
	s_add_u32 s42, s42, CAND_IJ@rel32@lo+4
	s_addc_u32 s43, s43, CAND_IJ@rel32@hi+12
	v_cndmask_b32_e64 v138, 0, 1, vcc
	v_cmp_lt_u32_e32 vcc, 7, v7
	s_movk_i32 s4, 0x80
	v_lshlrev_b32_e32 v130, 2, v3
	v_cndmask_b32_e64 v139, 0, 1, vcc
	v_cmp_lt_u32_e32 vcc, 8, v7
	v_and_b32_e32 v3, 7, v0
	v_mad_u64_u32 v[4:5], s[52:53], v6, s24, v[108:109]
	v_cndmask_b32_e64 v140, 0, 1, vcc
	v_cmp_lt_u32_e32 vcc, 9, v7
	v_ashrrev_i32_e32 v105, 31, v104
	s_movk_i32 s24, 0xf004
	v_cndmask_b32_e64 v141, 0, 1, vcc
	v_cmp_lt_u32_e32 vcc, 10, v7
	v_readlane_b32 s6, v252, 37
	v_lshlrev_b32_e32 v8, 2, v88
	v_cndmask_b32_e64 v142, 0, 1, vcc
	v_cmp_lt_u32_e32 vcc, 11, v7
	v_lshl_add_u64 v[102:103], v[0:1], 3, v[72:73]
	v_lshlrev_b32_e32 v1, 11, v6
	v_cndmask_b32_e64 v143, 0, 1, vcc
	v_cmp_lt_u32_e32 vcc, 12, v7
	v_and_b32_e32 v121, -16, v0
	v_sub_u32_e32 v122, v101, v104
	v_cndmask_b32_e64 v144, 0, 1, vcc
	v_cmp_lt_u32_e32 vcc, 13, v7
	v_lshl_add_u64 v[106:107], s[42:43], 0, v[88:89]
	v_lshlrev_b32_e32 v124, 5, v6
	v_cmp_gt_i32_e64 s[42:43], s4, v0
	v_cmp_eq_u32_e64 s[50:51], 0, v3
	v_mul_lo_u32 v3, v0, 12
	v_mul_lo_u32 v5, v6, s24
	v_cndmask_b32_e64 v145, 0, 1, vcc
	v_cmp_eq_u32_e32 vcc, 15, v7
	v_lshlrev_b64 v[6:7], 2, v[104:105]
	v_lshrrev_b32_e32 v0, 1, v0
	v_readlane_b32 s7, v252, 38
	v_readlane_b32 s23, v252, 31
	v_or_b32_e32 v120, 64, v88
	v_lshlrev_b32_e32 v123, 2, v121
	v_cmp_gt_u32_e64 s[40:41], 50, v88
	v_lshl_add_u32 v131, v88, 6, v4
	v_cmp_eq_u32_e64 s[52:53], 0, v88
	v_lshl_add_u64 v[114:115], v[104:105], 1, v[66:67]
	v_cndmask_b32_e64 v146, 0, 1, vcc
	v_lshl_add_u64 v[116:117], s[56:57], 0, v[6:7]
	v_lshl_add_u64 v[118:119], s[54:55], 0, v[6:7]
	v_add_u32_e32 v147, 0x2800, v108
	v_and_b32_e32 v148, 28, v0
	v_add_u32_e32 v149, v8, v1
	v_lshlrev_b32_e32 v150, 2, v2
	v_add_u32_e32 v151, v122, v3
	v_add_u32_e32 v152, v4, v5
	s_mov_b32 s74, s58
	v_readlane_b32 s5, v253, 15
	v_readlane_b32 s8, v253, 18
	v_readlane_b32 s9, v253, 19
	v_readlane_b32 s10, v253, 20
	v_readlane_b32 s11, v253, 21
	v_readlane_b32 s12, v253, 22
	v_readlane_b32 s13, v253, 23
	v_readlane_b32 s14, v253, 24
	v_readlane_b32 s15, v253, 25
	v_lshlrev_b32_e32 v232, 2, v104
	v_mov_b32_e32 v233, 0
	s_and_saveexec_b64 s[54:55], s[40:41]
	global_load_ubyte v233, v[106:107], off
	s_or_b64 exec, exec, s[54:55]
	s_mov_b32 s54, s74
	s_ashr_i32 s55, s74, 31
	s_lshl_b64 s[54:55], s[54:55], 13
	v_lshl_add_u64 v[218:219], v[102:103], 0, s[54:55]
	global_load_dwordx2 v[210:211], v[218:219], off sc1
	global_load_dwordx2 v[212:213], v[218:219], off offset:2048 sc1
	v_add_co_u32_e32 v218, vcc, 0x1000, v218
	s_nop 1
	v_addc_co_u32_e32 v219, vcc, 0, v219, vcc
	global_load_dwordx2 v[214:215], v[218:219], off sc1
	global_load_dwordx2 v[216:217], v[218:219], off offset:2048 sc1
	global_load_dwordx4 v[220:223], v[116:117], off
	global_load_dwordx4 v[224:227], v[118:119], off
	s_branch .LBB0_129
; DEVI void phase11(const Params& P, int l, int pass, char* smem) {
;     ...
;     float rs = rsqrtf((stat[4] + stat[5] + stat[6] + stat[7]) * (1.f / 1024.f) + 1e-5f);
;     float o[4];
; #pragma unroll
;     for (int i = 0; i < 4; ++i) o[i] = (y[i] - mu) * rs * g2[c + i] + b2[c + i];
;     *reinterpret_cast<float4*>(xr + c) = make_float4(o[0], o[1], o[2], o[3]);
;     store4bf(xb + (long)it * 1024 + c, o);
;   }
.LBB0_128:
	s_or_b64 exec, exec, s[54:55]
	s_waitcnt lgkmcnt(0)
	s_barrier
	ds_read_b128 v[6:9], v89 offset:30224
	s_ashr_i32 s77, s76, 31
	s_lshl_b64 s[54:55], s[76:77], 11
	s_add_i32 s74, s74, s23
	s_cmp_lt_i32 s74, s1
	s_waitcnt lgkmcnt(0)
	v_add_f32_e32 v6, v6, v7
	v_add_f32_e32 v6, v6, v8
	v_add_f32_e32 v6, v6, v9
	v_fmamk_f32 v6, v6, 0x3a800000, v184
	v_cmp_gt_f32_e32 vcc, s34, v6
	v_mul_f32_e32 v7, 0x4b800000, v6
	s_nop 0
	v_cndmask_b32_e32 v6, v6, v7, vcc
	v_rsq_f32_e32 v6, v6
	s_nop 0
	v_mul_f32_e32 v7, 0x45800000, v6
	v_cndmask_b32_e32 v12, v6, v7, vcc
	v_pk_mul_f32 v[14:15], v[4:5], v[12:13] op_sel_hi:[1,0]
	v_pk_mul_f32 v[2:3], v[2:3], v[12:13] op_sel_hi:[1,0]
	v_pk_fma_f32 v[4:5], v[220:221], v[14:15], v[224:225]
	v_pk_fma_f32 v[6:7], v[222:223], v[2:3], v[226:227]
	v_and_b32_sdwa v3, v4, v95 dst_sel:DWORD dst_unused:UNUSED_PAD src0_sel:WORD_1 src1_sel:DWORD
	v_and_b32_sdwa v2, v6, v95 dst_sel:DWORD dst_unused:UNUSED_PAD src0_sel:WORD_1 src1_sel:DWORD
	global_store_dwordx4 v[0:1], v[4:7], off
	v_add3_u32 v2, v6, v2, s39
	v_lshl_add_u64 v[0:1], v[114:115], 0, s[54:55]
	v_add3_u32 v4, v4, v3, s39
	v_and_b32_sdwa v3, v7, v95 dst_sel:DWORD dst_unused:UNUSED_PAD src0_sel:WORD_1 src1_sel:DWORD
	v_and_b32_sdwa v6, v5, v95 dst_sel:DWORD dst_unused:UNUSED_PAD src0_sel:WORD_1 src1_sel:DWORD
	v_add3_u32 v3, v7, v3, s39
	v_add3_u32 v5, v5, v6, s39
	v_and_b32_e32 v3, 0xffff0000, v3
	v_and_b32_e32 v5, 0xffff0000, v5
	v_or_b32_sdwa v3, v3, v2 dst_sel:DWORD dst_unused:UNUSED_PAD src0_sel:DWORD src1_sel:WORD_1
	v_or_b32_sdwa v2, v5, v4 dst_sel:DWORD dst_unused:UNUSED_PAD src0_sel:DWORD src1_sel:WORD_1
	global_store_dwordx2 v[0:1], v[2:3], off
	s_cbranch_scc0 .LBB0_275

; DEVI void phase11(const Params& P, int l, int pass, char* smem) {
;     ...
;     __syncthreads();
;     {
;       unsigned long long* s8 = reinterpret_cast<unsigned long long*>(const_cast<float*>(SC) + (long)lt * 2048);
;       unsigned long long* d8 = reinterpret_cast<unsigned long long*>(scl);
; #pragma unroll
;       for (int q = 0; q < 4; ++q)
;         d8[tid + 256 * q] = __hip_atomic_load(s8 + tid + 256 * q, __ATOMIC_RELAXED, __HIP_MEMORY_SCOPE_AGENT);
;     }
;     __syncthreads();
;     {
;       float v0[4], v1[4]; unsigned k0[4], k1[4], T[4];
; #pragma unroll
;       for (int li = 0; li < 4; ++li) {
;         const int Lx = w * 4 + li;
;         v0[li] = scl[Lx * 128 + lane]; v1[li] = scl[Lx * 128 + 64 + lane];
;         k0[li] = fkey(v0[li]); k1[li] = fkey(v1[li]); T[li] = 0;
;       }
.LBB0_137:
	s_barrier
	s_mov_b32 s62, 0
	s_mov_b32 s84, 0
	s_mov_b32 s24, 0
	s_mov_b32 s75, 0
	s_waitcnt vmcnt(2)
	ds_write_b64 v101, v[210:211]
	ds_write_b64 v101, v[212:213] offset:2048
	ds_write_b64 v101, v[214:215] offset:4096
	ds_write_b64 v101, v[216:217] offset:6144
	s_waitcnt lgkmcnt(0)
	s_barrier
	ds_read2st64_b32 v[10:11], v149 offset1:1
	ds_read2st64_b32 v[6:7], v149 offset0:2 offset1:3
	s_waitcnt lgkmcnt(1)
	v_and_b32_e32 v1, 0x7fffffff, v10
	v_and_b32_e32 v0, 0x7fffffff, v11
	v_xor_b32_e32 v2, -1, v10
	v_xor_b32_e32 v3, -1, v11
	v_pk_add_f32 v[0:1], v[0:1], 0 neg_lo:[1,1] neg_hi:[1,1]
	v_cmp_gt_i32_e32 vcc, 0, v11
	v_cmp_gt_i32_e64 s[54:55], 0, v10
	s_nop 0
	v_cndmask_b32_e32 v14, v0, v3, vcc
	v_cndmask_b32_e64 v15, v1, v2, s[54:55]
	s_waitcnt lgkmcnt(0)
	v_and_b32_e32 v1, 0x7fffffff, v6
	v_and_b32_e32 v0, 0x7fffffff, v7
	v_xor_b32_e32 v2, -1, v6
	v_xor_b32_e32 v3, -1, v7
	v_pk_add_f32 v[0:1], v[0:1], 0 neg_lo:[1,1] neg_hi:[1,1]
	v_cmp_gt_i32_e32 vcc, 0, v7
	v_cmp_gt_i32_e64 s[54:55], 0, v6
	s_nop 0
	v_cndmask_b32_e32 v12, v0, v3, vcc
	v_cndmask_b32_e64 v13, v1, v2, s[54:55]
	ds_read2st64_b32 v[2:3], v149 offset0:4 offset1:5
	s_waitcnt lgkmcnt(0)
	v_and_b32_e32 v1, 0x7fffffff, v2
	v_and_b32_e32 v0, 0x7fffffff, v3
	v_xor_b32_e32 v4, -1, v2
	v_xor_b32_e32 v5, -1, v3
	v_pk_add_f32 v[0:1], v[0:1], 0 neg_lo:[1,1] neg_hi:[1,1]
	v_cmp_gt_i32_e32 vcc, 0, v3
	v_cmp_gt_i32_e64 s[54:55], 0, v2
	s_nop 0
	v_cndmask_b32_e32 v8, v0, v5, vcc
	v_cndmask_b32_e64 v9, v1, v4, s[54:55]
	ds_read2st64_b32 v[0:1], v149 offset0:6 offset1:7
	s_waitcnt lgkmcnt(0)
	v_and_b32_e32 v5, 0x7fffffff, v0
	v_and_b32_e32 v4, 0x7fffffff, v1
	v_xor_b32_e32 v16, -1, v0
	v_xor_b32_e32 v17, -1, v1
	v_pk_add_f32 v[4:5], v[4:5], 0 neg_lo:[1,1] neg_hi:[1,1]
	v_cmp_gt_i32_e32 vcc, 0, v1
	v_cmp_gt_i32_e64 s[54:55], 0, v0
	s_nop 0
	v_cndmask_b32_e32 v4, v4, v17, vcc
	v_cndmask_b32_e64 v5, v5, v16, s[54:55]
	s_mov_b32 s54, 31

; DEVI void phase11(const Params& P, int l, int pass, char* smem) {
;     ...
;       svs[Lx * 16 + rank] = v; sis[Lx * 16 + rank] = id;
;     }
;     __builtin_amdgcn_wave_barrier();
;     {
;       float cv[2]; unsigned ck[2], T[2]; int ce[2];
;       const int cij = (lane < 50) ? (int)CAND_IJ[lane] : 0;
;       const int ci = cij >> 4, cj = cij & 15;
; #pragma unroll
;       for (int hi = 0; hi < 2; ++hi) {
;         const int h = w * 2 + hi;
;         T[hi] = 0;
;         cv[hi] = svs[(2 * h) * 16 + ci] + svs[(2 * h + 1) * 16 + cj];
;         ce[hi] = sis[(2 * h) * 16 + ci] * 128 + sis[(2 * h + 1) * 16 + cj];
;         ck[hi] = (lane < 50) ? fkey(cv[hi]) : 0u;
;       }
;       for (int b = 31; b >= KLOW; --b) {
; #pragma unroll
;         for (int hi = 0; hi < 2; ++hi) {
;           unsigned cand = T[hi] | (1u << b);
;           int cnt = __popcll(__ballot(ck[hi] >= cand));
;           if (cnt >= 16) T[hi] = cand;
;         }
;       }
.LBB0_247:
	s_or_b64 exec, exec, s[54:55]
	v_or_b32_e32 v1, v7, v121
	v_add3_u32 v1, v1, v6, v9
	v_add3_u32 v1, v1, v8, v11
	v_add3_u32 v1, v1, v10, v13
	v_add3_u32 v1, v1, v12, v15
	v_cmp_gt_f32_e32 vcc, v3, v4
	v_add3_u32 v1, v1, v14, v17
	s_nop 0
	v_addc_co_u32_e32 v1, vcc, v1, v16, vcc
	v_add3_u32 v1, v1, v19, v18
	v_add_lshl_u32 v0, v1, v0, 2
	ds_write2st64_b32 v0, v4, v5 offset0:46 offset1:50
	v_mov_b32_e32 v0, v233
	v_lshrrev_b32_e32 v1, 4, v0
	v_or_b32_e32 v1, v1, v109
	v_lshlrev_b32_e32 v1, 2, v1
	v_add_u32_e32 v2, 0x2c00, v1
	v_and_or_b32 v0, v0, 15, v109
	ds_read2_b32 v[4:5], v2 offset0:128 offset1:160
	v_lshlrev_b32_e32 v2, 2, v0
	v_add_u32_e32 v0, 0x2c00, v2
	ds_read2_b32 v[6:7], v0 offset0:144 offset1:176
	v_add_u32_e32 v0, 0x3000, v1
	s_waitcnt lgkmcnt(1)
	v_mov_b32_e32 v8, v5
	v_mov_b32_e32 v9, v4
	v_add_u32_e32 v2, 0x3000, v2
	s_waitcnt lgkmcnt(0)
	v_mov_b32_e32 v4, v7
	v_mov_b32_e32 v5, v6
	v_pk_add_f32 v[4:5], v[8:9], v[4:5]
	ds_read2_b32 v[0:1], v0 offset0:128 offset1:160
	v_not_b32_e32 v6, v5
	v_or_b32_e32 v7, 0x80000000, v5
	v_cmp_gt_i32_e32 vcc, 0, v5
	v_or_b32_e32 v8, 0x80000000, v4
	ds_read2_b32 v[2:3], v2 offset0:144 offset1:176
	v_cndmask_b32_e32 v6, v7, v6, vcc
	v_cndmask_b32_e64 v7, 0, v6, s[40:41]
	v_not_b32_e32 v6, v4
	v_cmp_gt_i32_e32 vcc, 0, v4
	s_nop 1
	v_cndmask_b32_e32 v6, v8, v6, vcc
	v_cmp_gt_i32_e32 vcc, 0, v7
	s_bcnt1_i32_b64 s24, vcc
	v_cndmask_b32_e64 v6, 0, v6, s[40:41]
	v_cmp_gt_u64_e64 s[54:55], s[24:25], 15
	s_and_b64 s[54:55], s[54:55], exec
	v_cmp_gt_i32_e32 vcc, 0, v6
	s_cselect_b32 s56, 0x80000000, 0
	s_bcnt1_i32_b64 s24, vcc
	v_cmp_gt_u64_e64 s[54:55], s[24:25], 15
	s_and_b64 s[54:55], s[54:55], exec
	s_cselect_b32 s57, 0x80000000, 0
	s_or_b32 s58, s56, 2.0
	v_cmp_le_u32_e32 vcc, s58, v7
	s_bcnt1_i32_b64 s24, vcc
	v_cmp_gt_u64_e64 s[54:55], s[24:25], 15
	s_and_b64 s[54:55], s[54:55], exec
	s_cselect_b32 s56, s58, s56
	s_or_b32 s58, s57, 2.0
	v_cmp_le_u32_e32 vcc, s58, v6
	s_bcnt1_i32_b64 s24, vcc
	v_cmp_gt_u64_e64 s[54:55], s[24:25], 15
	s_and_b64 s[54:55], s[54:55], exec
	s_cselect_b32 s57, s58, s57
	s_or_b32 s58, s56, 0x20000000
	v_cmp_le_u32_e32 vcc, s58, v7
	s_bcnt1_i32_b64 s24, vcc
	v_cmp_gt_u64_e64 s[54:55], s[24:25], 15
	s_and_b64 s[54:55], s[54:55], exec
	s_cselect_b32 s56, s58, s56
	s_or_b32 s58, s57, 0x20000000
	v_cmp_le_u32_e32 vcc, s58, v6
	s_bcnt1_i32_b64 s24, vcc
	v_cmp_gt_u64_e64 s[54:55], s[24:25], 15
	s_and_b64 s[54:55], s[54:55], exec
	s_cselect_b32 s57, s58, s57
	s_or_b32 s58, s56, 0x10000000
	v_cmp_le_u32_e32 vcc, s58, v7
	s_bcnt1_i32_b64 s24, vcc
	v_cmp_gt_u64_e64 s[54:55], s[24:25], 15
	s_and_b64 s[54:55], s[54:55], exec
	s_cselect_b32 s56, s58, s56
	s_or_b32 s58, s57, 0x10000000
	v_cmp_le_u32_e32 vcc, s58, v6
	s_bcnt1_i32_b64 s24, vcc
	v_cmp_gt_u64_e64 s[54:55], s[24:25], 15
	s_and_b64 s[54:55], s[54:55], exec
	s_cselect_b32 s57, s58, s57
	s_or_b32 s58, s56, 0x8000000
	v_cmp_le_u32_e32 vcc, s58, v7
	s_bcnt1_i32_b64 s24, vcc
	v_cmp_gt_u64_e64 s[54:55], s[24:25], 15
	s_and_b64 s[54:55], s[54:55], exec
	s_cselect_b32 s56, s58, s56
	s_or_b32 s58, s57, 0x8000000
	v_cmp_le_u32_e32 vcc, s58, v6
	s_bcnt1_i32_b64 s24, vcc
	v_cmp_gt_u64_e64 s[54:55], s[24:25], 15
	s_and_b64 s[54:55], s[54:55], exec
	s_cselect_b32 s57, s58, s57
	s_or_b32 s58, s56, 0x4000000
	v_cmp_le_u32_e32 vcc, s58, v7
	s_bcnt1_i32_b64 s24, vcc
	v_cmp_gt_u64_e64 s[54:55], s[24:25], 15
	s_and_b64 s[54:55], s[54:55], exec
	s_cselect_b32 s56, s58, s56
	s_or_b32 s58, s57, 0x4000000
	v_cmp_le_u32_e32 vcc, s58, v6
	s_bcnt1_i32_b64 s24, vcc
	v_cmp_gt_u64_e64 s[54:55], s[24:25], 15
	s_and_b64 s[54:55], s[54:55], exec
	s_cselect_b32 s57, s58, s57
	s_or_b32 s58, s56, 0x2000000
	v_cmp_le_u32_e32 vcc, s58, v7
	s_bcnt1_i32_b64 s24, vcc
	v_cmp_gt_u64_e64 s[54:55], s[24:25], 15
	s_and_b64 s[54:55], s[54:55], exec
	s_cselect_b32 s56, s58, s56
	s_or_b32 s58, s57, 0x2000000
	v_cmp_le_u32_e32 vcc, s58, v6
	s_bcnt1_i32_b64 s24, vcc
	v_cmp_gt_u64_e64 s[54:55], s[24:25], 15
	s_and_b64 s[54:55], s[54:55], exec
	s_cselect_b32 s57, s58, s57
	s_or_b32 s58, s56, 0x1000000
	v_cmp_le_u32_e32 vcc, s58, v7
	s_bcnt1_i32_b64 s24, vcc
	v_cmp_gt_u64_e64 s[54:55], s[24:25], 15
	s_and_b64 s[54:55], s[54:55], exec
	s_cselect_b32 s56, s58, s56
	s_or_b32 s58, s57, 0x1000000
	v_cmp_le_u32_e32 vcc, s58, v6
	s_bcnt1_i32_b64 s24, vcc
	v_cmp_gt_u64_e64 s[54:55], s[24:25], 15
	s_and_b64 s[54:55], s[54:55], exec
	s_cselect_b32 s57, s58, s57
	s_or_b32 s58, s56, 0x800000
	v_cmp_le_u32_e32 vcc, s58, v7
	s_bcnt1_i32_b64 s24, vcc
	v_cmp_gt_u64_e64 s[54:55], s[24:25], 15
	s_and_b64 s[54:55], s[54:55], exec
	s_cselect_b32 s56, s58, s56
	s_or_b32 s58, s57, 0x800000
	v_cmp_le_u32_e32 vcc, s58, v6
	s_bcnt1_i32_b64 s24, vcc
	v_cmp_gt_u64_e64 s[54:55], s[24:25], 15
	s_and_b64 s[54:55], s[54:55], exec
	s_cselect_b32 s57, s58, s57
	s_or_b32 s58, s56, 0x400000
	v_cmp_le_u32_e32 vcc, s58, v7
	s_bcnt1_i32_b64 s24, vcc
	v_cmp_gt_u64_e64 s[54:55], s[24:25], 15
	s_and_b64 s[54:55], s[54:55], exec
; DEVI void phase11(const Params& P, int l, int pass, char* smem) {
;     ...
;       for (int b = 31; b >= KLOW; --b) {
; #pragma unroll
;         for (int hi = 0; hi < 2; ++hi) {
;           unsigned cand = T[hi] | (1u << b);
;           int cnt = __popcll(__ballot(ck[hi] >= cand));
;           if (cnt >= 16) T[hi] = cand;
;         }
;       }
; #pragma unroll
;       for (int hi = 0; hi < 2; ++hi) {
;         const int h = w * 2 + hi;
;         const unsigned T2 = T[hi] + (1u << KLOW);
;         bool g = ck[hi] >= T2, q = (ck[hi] >= T[hi]) && !g && (lane < 50);
;         unsigned long long mg = __ballot(g), mq = __ballot(q);
;         int p = g ? __popcll(mg & ltmask) : __popcll(mg) + __popcll(mq & ltmask);
;         if ((g || q) && p < 16) { tops[h * 16 + p] = cv[hi]; tope[h * 16 + p] = ce[hi]; }
;       }
;     }
	s_cselect_b32 s56, s58, s56
	s_or_b32 s58, s57, 0x400000
	v_cmp_le_u32_e32 vcc, s58, v6
	s_bcnt1_i32_b64 s24, vcc
	v_cmp_gt_u64_e64 s[54:55], s[24:25], 15
	s_and_b64 s[54:55], s[54:55], exec
	s_cselect_b32 s57, s58, s57
	s_or_b32 s58, s56, 0x200000
	v_cmp_le_u32_e32 vcc, s58, v7
	s_bcnt1_i32_b64 s24, vcc
	v_cmp_gt_u64_e64 s[54:55], s[24:25], 15
	s_and_b64 s[54:55], s[54:55], exec
	s_cselect_b32 s56, s58, s56
	s_or_b32 s58, s57, 0x200000
	v_cmp_le_u32_e32 vcc, s58, v6
	s_bcnt1_i32_b64 s24, vcc
	v_cmp_gt_u64_e64 s[54:55], s[24:25], 15
	s_and_b64 s[54:55], s[54:55], exec
	s_cselect_b32 s57, s58, s57
	s_or_b32 s58, s56, 0x100000
	v_cmp_le_u32_e32 vcc, s58, v7
	s_bcnt1_i32_b64 s24, vcc
	v_cmp_gt_u64_e64 s[54:55], s[24:25], 15
	s_and_b64 s[54:55], s[54:55], exec
	s_cselect_b32 s56, s58, s56
	s_or_b32 s58, s57, 0x100000
	v_cmp_le_u32_e32 vcc, s58, v6
	s_bcnt1_i32_b64 s24, vcc
	v_cmp_gt_u64_e64 s[54:55], s[24:25], 15
	s_and_b64 s[54:55], s[54:55], exec
	s_cselect_b32 s57, s58, s57
	s_or_b32 s58, s56, 0x80000
	v_cmp_le_u32_e32 vcc, s58, v7
	s_bcnt1_i32_b64 s24, vcc
	v_cmp_gt_u64_e64 s[54:55], s[24:25], 15
	s_and_b64 s[54:55], s[54:55], exec
	s_cselect_b32 s56, s58, s56
	s_or_b32 s58, s57, 0x80000
	v_cmp_le_u32_e32 vcc, s58, v6
	s_bcnt1_i32_b64 s24, vcc
	v_cmp_gt_u64_e64 s[54:55], s[24:25], 15
	s_and_b64 s[54:55], s[54:55], exec
	s_cselect_b32 s57, s58, s57
	s_or_b32 s58, s56, 0x40000
	v_cmp_le_u32_e32 vcc, s58, v7
	s_bcnt1_i32_b64 s24, vcc
	v_cmp_gt_u64_e64 s[54:55], s[24:25], 15
	s_and_b64 s[54:55], s[54:55], exec
	s_cselect_b32 s56, s58, s56
	s_or_b32 s58, s57, 0x40000
	v_cmp_le_u32_e32 vcc, s58, v6
	s_bcnt1_i32_b64 s24, vcc
	v_cmp_gt_u64_e64 s[54:55], s[24:25], 15
	s_and_b64 s[54:55], s[54:55], exec
	s_cselect_b32 s57, s58, s57
	s_or_b32 s58, s56, 0x20000
	v_cmp_le_u32_e32 vcc, s58, v7
	s_bcnt1_i32_b64 s24, vcc
	v_cmp_gt_u64_e64 s[54:55], s[24:25], 15
	s_and_b64 s[54:55], s[54:55], exec
	s_cselect_b32 s56, s58, s56
	s_or_b32 s58, s57, 0x20000
	v_cmp_le_u32_e32 vcc, s58, v6
	s_bcnt1_i32_b64 s24, vcc
	v_cmp_gt_u64_e64 s[54:55], s[24:25], 15
	s_and_b64 s[54:55], s[54:55], exec
	s_cselect_b32 s57, s58, s57
	s_or_b32 s58, s56, 0x10000
	v_cmp_le_u32_e32 vcc, s58, v7
	s_bcnt1_i32_b64 s24, vcc
	v_cmp_gt_u64_e64 s[54:55], s[24:25], 15
	s_and_b64 s[54:55], s[54:55], exec
	s_cselect_b32 s56, s58, s56
	s_or_b32 s58, s57, 0x10000
	v_cmp_le_u32_e32 vcc, s58, v6
	s_bcnt1_i32_b64 s24, vcc
	v_cmp_gt_u64_e64 s[54:55], s[24:25], 15
	s_and_b64 s[54:55], s[54:55], exec
	s_cselect_b32 s57, s58, s57
	s_or_b32 s58, s56, 0x8000
	v_cmp_le_u32_e32 vcc, s58, v7
	s_bcnt1_i32_b64 s24, vcc
	v_cmp_gt_u64_e64 s[54:55], s[24:25], 15
	s_and_b64 s[54:55], s[54:55], exec
	s_cselect_b32 s56, s58, s56
	s_or_b32 s58, s57, 0x8000
	v_cmp_le_u32_e32 vcc, s58, v6
	s_bcnt1_i32_b64 s24, vcc
	v_cmp_gt_u64_e64 s[54:55], s[24:25], 15
	s_and_b64 s[54:55], s[54:55], exec
	s_cselect_b32 s57, s58, s57
	s_or_b32 s58, s56, 0x4000
	v_cmp_le_u32_e32 vcc, s58, v7
	s_bcnt1_i32_b64 s24, vcc
	v_cmp_gt_u64_e64 s[54:55], s[24:25], 15
	s_and_b64 s[54:55], s[54:55], exec
	s_cselect_b32 s56, s58, s56
	s_or_b32 s58, s57, 0x4000
	v_cmp_le_u32_e32 vcc, s58, v6
	s_bcnt1_i32_b64 s24, vcc
	v_cmp_gt_u64_e64 s[54:55], s[24:25], 15
	s_and_b64 s[54:55], s[54:55], exec
	s_cselect_b32 s57, s58, s57
	s_or_b32 s58, s56, 0x2000
	v_cmp_le_u32_e32 vcc, s58, v7
	s_bcnt1_i32_b64 s24, vcc
	v_cmp_gt_u64_e64 s[54:55], s[24:25], 15
	s_and_b64 s[54:55], s[54:55], exec
	s_cselect_b32 s56, s58, s56
	s_or_b32 s58, s57, 0x2000
	v_cmp_le_u32_e32 vcc, s58, v6
	s_bcnt1_i32_b64 s24, vcc
	v_cmp_gt_u64_e64 s[54:55], s[24:25], 15
	s_and_b64 s[54:55], s[54:55], exec
	s_cselect_b32 s62, s58, s57
	s_or_b32 s57, s56, 0x1000
	v_cmp_le_u32_e32 vcc, s57, v7
	s_bcnt1_i32_b64 s24, vcc
	v_cmp_gt_u64_e64 s[54:55], s[24:25], 15
	s_and_b64 s[54:55], s[54:55], exec
	s_cselect_b32 s24, s57, s56
	s_add_i32 s56, s24, 0x1000
	v_cmp_le_u32_e64 s[54:55], s56, v7
	v_cmp_gt_u32_e64 s[58:59], s56, v7
	v_cmp_le_u32_e64 s[56:57], s24, v7
	s_and_b64 s[56:57], s[56:57], s[58:59]
	s_and_b64 s[60:61], s[40:41], s[56:57]
	s_or_b32 s63, s62, 0x1000
	v_cndmask_b32_e64 v7, 0, 1, s[60:61]
	v_cmp_le_u32_e32 vcc, s63, v6
	v_cmp_ne_u32_e64 s[56:57], 0, v7
	s_and_saveexec_b64 s[64:65], s[58:59]
	s_xor_b64 s[58:59], exec, s[64:65]
	v_and_b32_e32 v8, s56, v100
	v_and_b32_e32 v7, s57, v91
	v_bcnt_u32_b32 v8, v8, 0
	s_bcnt1_i32_b64 s24, s[54:55]
	v_bcnt_u32_b32 v7, v7, v8
	v_add_u32_e32 v7, s24, v7
	s_andn2_saveexec_b64 s[56:57], s[58:59]
	v_and_b32_e32 v8, s54, v100
	v_and_b32_e32 v7, s55, v91
	v_bcnt_u32_b32 v8, v8, 0
	v_bcnt_u32_b32 v7, v7, v8
	s_or_b64 exec, exec, s[56:57]
	s_or_b64 s[56:57], s[54:55], s[60:61]
	v_cmp_gt_u32_e64 s[54:55], 16, v7
	s_and_b64 s[56:57], s[56:57], s[54:55]
	s_and_saveexec_b64 s[54:55], s[56:57]
	s_cbranch_execz .LBB0_255
	s_waitcnt lgkmcnt(0)
	v_lshl_add_u32 v0, v0, 7, v2
	v_or_b32_e32 v2, v7, v124
	v_lshlrev_b32_e32 v2, 2, v2
	ds_write2st64_b32 v2, v5, v0 offset0:40 offset1:42

; DEVI void phase11(const Params& P, int l, int pass, char* smem) {
;     ...
;     f32x2 xv[8];
;     {
;       const float4* xp = reinterpret_cast<const float4*>(xr + lane * 16);
; #pragma unroll
;       for (int q = 0; q < 4; ++q) {
;         float4 a = xp[q];
;         xv[2 * q] = f32x2{a.x, a.y}; xv[2 * q + 1] = f32x2{a.z, a.w};
;       }
;     }
;     f32x2 oacc[8];
; #pragma unroll
;     for (int q = 0; q < 8; ++q) oacc[q] = f32x2{0.f, 0.f};
; #pragma unroll 1
;     for (int p0 = 0; p0 < 32; p0 += 8) {
;       uint4 ru[8], rv[8];
; #pragma unroll
;       for (int i = 0; i < 8; ++i) {
;         int e = tope[w * 32 + p0 + i];
;         ru[i] = *reinterpret_cast<const uint4*>(UT + (long)e * 1024 + lane * 16);
;         rv[i] = *reinterpret_cast<const uint4*>(VTb + (long)e * 1024 + lane * 16);
.LBB0_263:
	s_or_b64 exec, exec, s[54:55]
	s_lshl_b32 s24, s77, 12
	s_lshl_b32 s54, s77, 5
	s_or_b32 s24, s24, s83
	s_add_i32 s56, s54, s83
	s_and_b64 s[54:55], s[78:79], exec
	s_cselect_b32 s54, s24, s56
	s_ashr_i32 s55, s54, 31
	s_lshl_b64 s[54:55], s[54:55], 12
	s_and_b64 s[56:57], s[78:79], exec
	s_cselect_b32 s56, s28, s33
	s_cselect_b32 s24, s29, s93
	s_add_u32 s54, s56, s54
	s_addc_u32 s55, s24, s55
	s_waitcnt lgkmcnt(0)
	s_barrier
	global_load_dwordx4 v[0:3], v150, s[54:55] offset:48
	global_load_dwordx4 v[4:7], v150, s[54:55] offset:32
	global_load_dwordx4 v[8:11], v150, s[54:55] offset:16
	global_load_dwordx4 v[12:15], v150, s[54:55]
	global_load_dwordx4 v[228:231], v232, s[54:55]
	v_mov_b32_e32 v16, 0
	s_mov_b32 s24, -8
	v_mov_b32_e32 v153, v147
	v_mov_b32_e32 v17, v16
	v_mov_b32_e32 v18, v16
	v_mov_b32_e32 v19, v16
	v_mov_b32_e32 v28, v16
	v_mov_b32_e32 v29, v16
	v_mov_b32_e32 v30, v16
	v_mov_b32_e32 v31, v16
	v_mov_b32_e32 v24, v16
	v_mov_b32_e32 v25, v16
	v_mov_b32_e32 v26, v16
	v_mov_b32_e32 v27, v16
	v_mov_b32_e32 v20, v16
	v_mov_b32_e32 v21, v16
	v_mov_b32_e32 v22, v16
	v_mov_b32_e32 v23, v16
	s_branch .LBB0_265

; DEVI void phase11(const Params& P, int l, int pass, char* smem) {
;     ...
;     {
;       float4* rwp = reinterpret_cast<float4*>(red + w * 1024 + lane * 16);
; #pragma unroll
;       for (int q = 0; q < 4; ++q) rwp[q] = make_float4(oacc[2 * q].x, oacc[2 * q].y, oacc[2 * q + 1].x, oacc[2 * q + 1].y);
;     }
;     __syncthreads();
;     const int c = tid * 4;
;     float y[4];
;     {
;       float4 xx = *reinterpret_cast<const float4*>(xr + c);
;       float4 r0 = *reinterpret_cast<const float4*>(red + c);
;       float4 r1 = *reinterpret_cast<const float4*>(red + 1024 + c);
;       float4 r2 = *reinterpret_cast<const float4*>(red + 2048 + c);
;       float4 r3 = *reinterpret_cast<const float4*>(red + 3072 + c);
;       y[0] = ALPHA * xx.x + (r0.x + r1.x + r2.x + r3.x);
;       y[1] = ALPHA * xx.y + (r0.y + r1.y + r2.y + r3.y);
;       y[2] = ALPHA * xx.z + (r0.z + r1.z + r2.z + r3.z);
;       y[3] = ALPHA * xx.w + (r0.w + r1.w + r2.w + r3.w);
;     }
;     float s = wave_sum(y[0] + y[1] + y[2] + y[3]);
;     if (lane == 0) stat[w] = s;
.LBB0_271:
	v_lshl_add_u64 v[0:1], v[104:105], 2, s[54:55]
	ds_write_b128 v131, v[16:19] offset:13824
	ds_write_b128 v131, v[28:31] offset:13840
	ds_write_b128 v131, v[24:27] offset:13856
	ds_write_b128 v131, v[20:23] offset:13872
	s_waitcnt lgkmcnt(0)
	s_barrier
	s_add_i32 s56, s74, s23
	s_cmp_lt_i32 s56, s1
	s_cselect_b32 s56, s56, s74
	s_ashr_i32 s57, s56, 31
	s_lshl_b64 s[56:57], s[56:57], 13
	v_lshl_add_u64 v[218:219], v[102:103], 0, s[56:57]
	global_load_dwordx2 v[210:211], v[218:219], off sc1
	global_load_dwordx2 v[212:213], v[218:219], off offset:2048 sc1
	v_add_co_u32_e32 v218, vcc, 0x1000, v218
	s_nop 1
	v_addc_co_u32_e32 v219, vcc, 0, v219, vcc
	global_load_dwordx2 v[214:215], v[218:219], off sc1
	global_load_dwordx2 v[216:217], v[218:219], off offset:2048 sc1
	ds_read_b128 v[8:11], v151 offset:13824
	ds_read_b128 v[12:15], v151 offset:17920
	ds_read_b128 v[16:19], v151 offset:22016
	ds_read_b128 v[20:23], v151 offset:26112
	s_waitcnt lgkmcnt(2)
	v_pk_add_f32 v[2:3], v[8:9], v[12:13]
	v_pk_add_f32 v[8:9], v[10:11], v[14:15]
	s_waitcnt lgkmcnt(1)
	v_pk_add_f32 v[2:3], v[2:3], v[16:17]
	v_pk_add_f32 v[8:9], v[8:9], v[18:19]
	s_waitcnt lgkmcnt(0)
	v_pk_add_f32 v[2:3], v[2:3], v[20:21]
	v_pk_add_f32 v[8:9], v[8:9], v[22:23]
	v_pk_fma_f32 v[4:5], v[228:229], s[92:93], v[2:3] op_sel_hi:[1,0,1]
	v_pk_fma_f32 v[2:3], v[230:231], s[92:93], v[8:9] op_sel_hi:[1,0,1]
	v_add_f32_e32 v6, v4, v5
	v_add_f32_e32 v6, v6, v2
	v_add_f32_e32 v6, v6, v3
	ds_bpermute_b32 v7, v125, v6
	s_waitcnt lgkmcnt(0)
	v_add_f32_e32 v6, v6, v7
	ds_bpermute_b32 v7, v126, v6
	s_waitcnt lgkmcnt(0)
	v_add_f32_e32 v6, v6, v7
	ds_bpermute_b32 v7, v127, v6
	s_waitcnt lgkmcnt(0)
	v_add_f32_e32 v6, v6, v7
	ds_bpermute_b32 v7, v128, v6
	s_waitcnt lgkmcnt(0)
	v_add_f32_e32 v6, v6, v7
	ds_bpermute_b32 v7, v129, v6
	s_waitcnt lgkmcnt(0)
	v_add_f32_e32 v6, v6, v7
	ds_bpermute_b32 v7, v130, v6
	s_and_saveexec_b64 s[54:55], s[52:53]
	s_cbranch_execz .LBB0_273
	s_waitcnt lgkmcnt(0)
	v_add_f32_e32 v6, v6, v7
	ds_write_b32 v152, v6 offset:30208
